# E8b + group-B tile stores moved right after QK (overlap softmax) + softmax row sums moved to the head of the PV segment (4 partial sums)
# baseline (speedup 1.0000x reference)
; #define MFMA(a, b, c) __builtin_amdgcn_mfma_f32_32x32x16_bf16((a), (b), (c), 0, 0, 0)
; DI int crow(int reg, int hh) { return (reg & 3) + 8 * (reg >> 2) + 4 * hh; }
; DI void attn_phase(const Params& p, const u16* proj, const char* prep, u16* obuf, char* smem) {
;     ...
;       __builtin_amdgcn_s_setprio(1);
; #pragma unroll
;       for (int kti = 0; kti < 2; ++kti) {
;         st[kti] = zero16();
; #pragma unroll
;         for (int s = 0; s < 8; ++s) {
;           const bf16x8 a = ld16(Ks + (jh * 64 + kti * 32 + l31) * 136 + s * 16 + hh * 8);
;           st[kti] = MFMA(a, Qf[s], st[kti]);
;         }
;       }
;       __builtin_amdgcn_s_setprio(0);
;       constexpr float SC = 0.08838834764831845f * 1.4426950408889634f;
;       if ((kt + 1) * 64 > nkeys) {
; #pragma unroll
;         for (int kti = 0; kti < 2; ++kti)
; #pragma unroll
;           for (int reg = 0; reg < 16; ++reg)
;             if (kt * 64 + kti * 32 + crow(reg, hh) >= nkeys) st[kti][reg] = -1e30f;
;       }
;     ...
;       if (grpB && kt + 1 < nt) { sstore((kt + 1) & 1); if (kt + 2 < nt) gload(kt + 2); }
.LBB0_1033:
	s_bitcmp1_b32 s67, 0
	s_cselect_b32 s10, 0x11800, 0
	s_add_i32 s85, s10, 0
	s_setprio 2
	v_lshl_add_u32 v233, v164, 1, s85
	v_add_u32_e32 v232, v233, v224
	ds_read_b128 v[64:67], v232
	ds_read_b128 v[68:71], v232 offset:32
	ds_read_b128 v[72:75], v232 offset:64
	ds_read_b128 v[76:79], v232 offset:96
	ds_read_b128 v[236:239], v232 offset:128
	ds_read_b128 v[240:243], v232 offset:160
	ds_read_b128 v[244:247], v232 offset:192
	s_waitcnt lgkmcnt(6)
	v_mfma_f32_32x32x16_bf16 v[80:95], v[64:67], v[96:99], 0
	s_waitcnt lgkmcnt(5)
	v_mfma_f32_32x32x16_bf16 v[80:95], v[68:71], v[100:103], v[80:95]
	ds_read_b128 v[64:67], v232 offset:224
	s_waitcnt lgkmcnt(5)
	v_mfma_f32_32x32x16_bf16 v[80:95], v[72:75], v[104:107], v[80:95]
	s_waitcnt lgkmcnt(4)
	v_mfma_f32_32x32x16_bf16 v[80:95], v[76:79], v[108:111], v[80:95]
	ds_read_b128 v[68:71], v232 offset:8704
	s_waitcnt lgkmcnt(4)
	v_mfma_f32_32x32x16_bf16 v[80:95], v[236:239], v[112:115], v[80:95]
	ds_read_b128 v[236:239], v232 offset:8736
	s_waitcnt lgkmcnt(4)
	v_mfma_f32_32x32x16_bf16 v[80:95], v[240:243], v[116:119], v[80:95]
	ds_read_b128 v[240:243], v232 offset:8768
	s_waitcnt lgkmcnt(4)
	v_mfma_f32_32x32x16_bf16 v[80:95], v[244:247], v[120:123], v[80:95]
	ds_read_b128 v[244:247], v232 offset:8800
	s_waitcnt lgkmcnt(4)
	v_mfma_f32_32x32x16_bf16 v[80:95], v[64:67], v[124:127], v[80:95]
	s_waitcnt lgkmcnt(3)
	v_mfma_f32_32x32x16_bf16 v[64:79], v[68:71], v[96:99], 0
	s_waitcnt lgkmcnt(2)
	v_mfma_f32_32x32x16_bf16 v[64:79], v[236:239], v[100:103], v[64:79]
	ds_read_b128 v[236:239], v232 offset:8832
	s_waitcnt lgkmcnt(2)
	v_mfma_f32_32x32x16_bf16 v[64:79], v[240:243], v[104:107], v[64:79]
	ds_read_b128 v[240:243], v232 offset:8864
	s_waitcnt lgkmcnt(2)
	v_mfma_f32_32x32x16_bf16 v[64:79], v[244:247], v[108:111], v[64:79]
	ds_read_b128 v[244:247], v232 offset:8896
	s_waitcnt lgkmcnt(2)
	v_mfma_f32_32x32x16_bf16 v[64:79], v[236:239], v[112:115], v[64:79]
	ds_read_b128 v[236:239], v232 offset:8928
	s_waitcnt lgkmcnt(2)
	v_mfma_f32_32x32x16_bf16 v[64:79], v[240:243], v[116:119], v[64:79]
	s_waitcnt lgkmcnt(1)
	v_mfma_f32_32x32x16_bf16 v[64:79], v[244:247], v[120:123], v[64:79]
	s_waitcnt lgkmcnt(0)
	v_mfma_f32_32x32x16_bf16 v[64:79], v[236:239], v[124:127], v[64:79]
	s_setprio 0
	s_andn2_b64 vcc, exec, s[76:77]
	s_cbranch_vccnz .Lss_skip
	s_add_i32 s13, s67, 1
	s_cmp_lt_i32 s13, s65
	s_cbranch_scc0 .Lss_skip
	s_bitcmp1_b32 s13, 0
	s_cselect_b32 s13, 0x11800, 0
	v_add3_u32 v235, s13, v201, v162
	s_waitcnt vmcnt(7)
	ds_write_b128 v235, v[128:131]
	v_add3_u32 v248, s13, v203, v182
	s_waitcnt vmcnt(5)
	ds_write_b128 v248, v[132:135] offset:34816
	v_add3_u32 v235, s13, v205, v162
	s_waitcnt vmcnt(3)
	ds_write_b128 v235, v[136:139]
	v_add3_u32 v248, s13, v207, v182
	s_waitcnt vmcnt(1)
	ds_write_b128 v248, v[140:143] offset:34816
	v_add3_u32 v235, s13, v211, v162
	ds_write_b128 v235, v[144:147]
	v_add3_u32 v248, s13, v213, v182
	ds_write_b128 v248, v[148:151] offset:34816
	v_add3_u32 v235, s13, v215, v162
	ds_write_b128 v235, v[152:155]
	v_add3_u32 v248, s13, v217, v182
	s_waitcnt vmcnt(0)
	ds_write_b128 v248, v[156:159] offset:34816
.Lss_skip:
	s_sub_i32 s10, s78, 64
	s_cmp_le_i32 s10, s66
	s_cbranch_scc1 .LBB0_1035
	v_add_u32_e32 v232, s78, v222
	v_add_u32_e32 v235, 0xffffff80, v232
	v_cmp_gt_i32_e32 vcc, s66, v235
	v_add_u32_e32 v235, 0xffffff81, v232
	v_cmp_gt_i32_e64 s[10:11], s66, v235
	s_or_b64 vcc, s[10:11], vcc
	v_add_u32_e32 v235, 0xffffff82, v232
	v_cndmask_b32_e32 v80, v229, v80, vcc
	v_cmp_gt_i32_e32 vcc, s66, v235
	v_add_u32_e32 v235, 0xffffff83, v232
	v_cndmask_b32_e64 v81, v229, v81, s[10:11]
	v_cndmask_b32_e32 v82, v229, v82, vcc
	v_cmp_gt_i32_e32 vcc, s66, v235
	v_add_u32_e32 v235, 0xffffff88, v232
	s_nop 0
	v_cndmask_b32_e32 v83, v229, v83, vcc
	v_cmp_gt_i32_e32 vcc, s66, v235
	v_add_u32_e32 v235, 0xffffff89, v232
	s_nop 0
	v_cndmask_b32_e32 v84, v229, v84, vcc
	v_cmp_gt_i32_e32 vcc, s66, v235
	v_add_u32_e32 v235, 0xffffff8a, v232
	s_nop 0
	v_cndmask_b32_e32 v85, v229, v85, vcc
	v_cmp_gt_i32_e32 vcc, s66, v235
	v_add_u32_e32 v235, 0xffffff8b, v232
	s_nop 0
	v_cndmask_b32_e32 v86, v229, v86, vcc
	v_cmp_gt_i32_e32 vcc, s66, v235
	v_add_u32_e32 v235, 0xffffff90, v232
	s_nop 0
	v_cndmask_b32_e32 v87, v229, v87, vcc
	v_cmp_gt_i32_e32 vcc, s66, v235
	v_add_u32_e32 v235, 0xffffff91, v232
	s_nop 0
	v_cndmask_b32_e32 v88, v229, v88, vcc
	v_cmp_gt_i32_e32 vcc, s66, v235
	v_add_u32_e32 v235, 0xffffff92, v232
	s_nop 0
	v_cndmask_b32_e32 v89, v229, v89, vcc
	v_cmp_gt_i32_e32 vcc, s66, v235
	v_add_u32_e32 v235, 0xffffff93, v232
	s_nop 0
	v_cndmask_b32_e32 v90, v229, v90, vcc
	v_cmp_gt_i32_e32 vcc, s66, v235
	v_add_u32_e32 v235, 0xffffff98, v232
	s_nop 0
	v_cndmask_b32_e32 v91, v229, v91, vcc
	v_cmp_gt_i32_e32 vcc, s66, v235
	v_add_u32_e32 v235, 0xffffff99, v232
	s_nop 0
	v_cndmask_b32_e32 v92, v229, v92, vcc
	v_cmp_gt_i32_e32 vcc, s66, v235
	v_add_u32_e32 v235, 0xffffff9a, v232
	s_nop 0
	v_cndmask_b32_e32 v93, v229, v93, vcc
	v_cmp_gt_i32_e32 vcc, s66, v235
	v_add_u32_e32 v235, 0xffffff9b, v232
	s_nop 0
	v_cndmask_b32_e32 v94, v229, v94, vcc
	v_cmp_gt_i32_e32 vcc, s66, v235
	v_add_u32_e32 v235, 0xffffffa0, v232
	v_cmp_gt_i32_e64 s[10:11], s66, v235
	v_add_u32_e32 v235, 0xffffffa1, v232
	v_cmp_gt_i32_e64 s[12:13], s66, v235
	v_add_u32_e32 v235, 0xffffffa2, v232
	v_cmp_gt_i32_e64 s[14:15], s66, v235
	v_add_u32_e32 v235, 0xffffffa3, v232
	v_cmp_gt_i32_e64 s[16:17], s66, v235
	v_add_u32_e32 v235, 0xffffffa8, v232
	v_cmp_gt_i32_e64 s[18:19], s66, v235
	v_add_u32_e32 v235, 0xffffffa9, v232
	v_cmp_gt_i32_e64 s[20:21], s66, v235
	v_add_u32_e32 v235, 0xffffffaa, v232
	v_cmp_gt_i32_e64 s[22:23], s66, v235
; DI int crow(int reg, int hh) { return (reg & 3) + 8 * (reg >> 2) + 4 * hh; }
; DI void attn_phase(const Params& p, const u16* proj, const char* prep, u16* obuf, char* smem) {
;     ...
;       if ((kt + 1) * 64 > nkeys) {
; #pragma unroll
;         for (int kti = 0; kti < 2; ++kti)
; #pragma unroll
;           for (int reg = 0; reg < 16; ++reg)
;             if (kt * 64 + kti * 32 + crow(reg, hh) >= nkeys) st[kti][reg] = -1e30f;
;       }
;       float mx = -1e30f;
; #pragma unroll
;       for (int kti = 0; kti < 2; ++kti)
; #pragma unroll
;         for (int reg = 0; reg < 16; ++reg) mx = fmaxf(mx, st[kti][reg]);
;       mx = fmaxf(mx, __shfl_xor(mx, 32)) * SC;
;       const bool bump = __any(mx > m + 8.f);
;       const float mn = bump ? fmaxf(m, mx) : m;
;       float rs = 0.f;
; #pragma unroll
;       for (int kti = 0; kti < 2; ++kti)
; #pragma unroll
;         for (int reg = 0; reg < 16; ++reg) {
;           const float pv = __builtin_amdgcn_exp2f(st[kti][reg] * SC - mn);
;           st[kti][reg] = pv; rs += pv;
;         }
;       rs += __shfl_xor(rs, 32);
;       if (bump) {
;         const float alpha = __builtin_amdgcn_exp2f(m - mn);
;         l *= alpha;
; #pragma unroll
;         for (int vt = 0; vt < 4; ++vt)
; #pragma unroll
;           for (int reg = 0; reg < 16; ++reg) O[vt][reg] *= alpha;
;       }
;       l += rs; m = mn;
	v_add_u32_e32 v235, 0xffffffab, v232
	v_cmp_gt_i32_e64 s[24:25], s66, v235
	v_add_u32_e32 v235, 0xffffffb0, v232
	v_cmp_gt_i32_e64 s[26:27], s66, v235
	v_add_u32_e32 v235, 0xffffffb1, v232
	v_cmp_gt_i32_e64 s[28:29], s66, v235
	v_add_u32_e32 v235, 0xffffffb2, v232
	v_cmp_gt_i32_e64 s[30:31], s66, v235
	v_add_u32_e32 v235, 0xffffffb3, v232
	v_cmp_gt_i32_e64 s[34:35], s66, v235
	v_add_u32_e32 v235, 0xffffffb8, v232
	v_cmp_gt_i32_e64 s[36:37], s66, v235
	v_add_u32_e32 v235, 0xffffffb9, v232
	v_cmp_gt_i32_e64 s[38:39], s66, v235
	v_add_u32_e32 v235, 0xffffffba, v232
	v_add_u32_e32 v232, 0xffffffbb, v232
	v_cmp_gt_i32_e64 s[40:41], s66, v235
	v_cmp_gt_i32_e64 s[42:43], s66, v232
	s_or_b64 s[40:41], s[42:43], s[40:41]
	s_or_b64 s[38:39], s[40:41], s[38:39]
	s_or_b64 s[36:37], s[38:39], s[36:37]
	s_or_b64 s[34:35], s[36:37], s[34:35]
	s_or_b64 s[30:31], s[34:35], s[30:31]
	s_or_b64 s[28:29], s[30:31], s[28:29]
	s_or_b64 s[26:27], s[28:29], s[26:27]
	s_or_b64 s[24:25], s[26:27], s[24:25]
	s_or_b64 s[22:23], s[24:25], s[22:23]
	s_or_b64 s[20:21], s[22:23], s[20:21]
	s_or_b64 s[18:19], s[20:21], s[18:19]
	s_or_b64 s[16:17], s[18:19], s[16:17]
	s_or_b64 s[14:15], s[16:17], s[14:15]
	s_or_b64 s[12:13], s[14:15], s[12:13]
	s_or_b64 s[10:11], s[12:13], s[10:11]
	s_or_b64 vcc, s[10:11], vcc
	v_cndmask_b32_e64 v79, v229, v79, s[42:43]
	v_cndmask_b32_e64 v78, v229, v78, s[40:41]
	v_cndmask_b32_e64 v77, v229, v77, s[38:39]
	v_cndmask_b32_e64 v76, v229, v76, s[36:37]
	v_cndmask_b32_e64 v75, v229, v75, s[34:35]
	v_cndmask_b32_e64 v74, v229, v74, s[30:31]
	v_cndmask_b32_e64 v73, v229, v73, s[28:29]
	v_cndmask_b32_e64 v72, v229, v72, s[26:27]
	v_cndmask_b32_e64 v71, v229, v71, s[24:25]
	v_cndmask_b32_e64 v70, v229, v70, s[22:23]
	v_cndmask_b32_e64 v69, v229, v69, s[20:21]
	v_cndmask_b32_e64 v68, v229, v68, s[18:19]
	v_cndmask_b32_e64 v67, v229, v67, s[16:17]
	v_cndmask_b32_e64 v66, v229, v66, s[14:15]
	v_cndmask_b32_e64 v65, v229, v65, s[12:13]
	v_cndmask_b32_e64 v64, v229, v64, s[10:11]
	v_cndmask_b32_e32 v95, v229, v95, vcc
.LBB0_1035:
	s_mov_b32 s10, 0xf149f2ca
	v_max3_f32 v232, v80, s10, v81
	v_max3_f32 v232, v232, v82, v83
	v_max3_f32 v232, v232, v84, v85
	v_max3_f32 v232, v232, v86, v87
	v_max3_f32 v232, v232, v88, v89
	v_max3_f32 v232, v232, v90, v91
	v_max3_f32 v232, v232, v92, v93
	v_max3_f32 v232, v232, v94, v95
	v_max3_f32 v232, v232, v64, v65
	v_max3_f32 v232, v232, v66, v67
	v_max3_f32 v232, v232, v68, v69
	v_max3_f32 v232, v232, v70, v71
	v_max3_f32 v232, v232, v72, v73
	v_max3_f32 v232, v232, v74, v75
	v_max3_f32 v232, v232, v76, v77
	v_max3_f32 v232, v232, v78, v79
	ds_bpermute_b32 v235, v181, v232
	v_add_f32_e32 v236, 0x41000000, v234
	v_max_f32_e32 v237, v234, v234
	s_waitcnt lgkmcnt(0)
	v_max_f32_e32 v235, v235, v235
	v_max_f32_e32 v232, v232, v235
	v_mul_f32_e32 v232, 0x3e0293ee, v232
	v_cmp_gt_f32_e32 vcc, v232, v236
	s_cmp_eq_u64 vcc, 0
	v_max_f32_e32 v243, v237, v232
	s_cselect_b64 s[10:11], -1, 0
	v_cndmask_b32_e64 v232, v243, v234, s[10:11]
	v_fma_f32 v80, v80, s33, -v232
	v_exp_f32_e32 v235, v80
	v_fma_f32 v80, v81, s33, -v232
	v_exp_f32_e32 v236, v80
	v_fma_f32 v80, v82, s33, -v232
	v_exp_f32_e32 v237, v80
	v_fma_f32 v80, v83, s33, -v232
	v_exp_f32_e32 v238, v80
	v_fma_f32 v81, v84, s33, -v232
	v_exp_f32_e32 v239, v81
	v_fma_f32 v81, v85, s33, -v232
	v_exp_f32_e32 v240, v81
	v_fma_f32 v81, v86, s33, -v232
	v_exp_f32_e32 v241, v81
	v_fma_f32 v81, v87, s33, -v232
	v_exp_f32_e32 v242, v81
	v_fma_f32 v80, v88, s33, -v232
	v_exp_f32_e32 v80, v80
	v_fma_f32 v81, v89, s33, -v232
	v_exp_f32_e32 v81, v81
	v_fma_f32 v82, v90, s33, -v232
	v_exp_f32_e32 v82, v82
	v_fma_f32 v83, v91, s33, -v232
	v_exp_f32_e32 v83, v83
	v_fma_f32 v84, v92, s33, -v232
	v_exp_f32_e32 v84, v84
	v_fma_f32 v85, v93, s33, -v232
	v_exp_f32_e32 v85, v85
	v_fma_f32 v87, v94, s33, -v232
	v_exp_f32_e32 v87, v87
	v_fma_f32 v88, v95, s33, -v232
	v_exp_f32_e32 v89, v88
	v_fma_f32 v64, v64, s33, -v232
	v_exp_f32_e32 v86, v64
	v_fma_f32 v64, v65, s33, -v232
	v_exp_f32_e32 v88, v64
	v_fma_f32 v64, v66, s33, -v232
	v_exp_f32_e32 v90, v64
	v_fma_f32 v64, v67, s33, -v232
	v_exp_f32_e32 v91, v64
	v_fma_f32 v65, v68, s33, -v232
	v_exp_f32_e32 v92, v65
	v_fma_f32 v65, v69, s33, -v232
	v_exp_f32_e32 v93, v65
	v_fma_f32 v65, v70, s33, -v232
	v_exp_f32_e32 v94, v65
	v_fma_f32 v65, v71, s33, -v232
	v_exp_f32_e32 v95, v65
	v_fma_f32 v65, v72, s33, -v232
	v_exp_f32_e32 v66, v65
	v_fma_f32 v65, v73, s33, -v232
	v_exp_f32_e32 v67, v65
	v_fma_f32 v65, v74, s33, -v232
	v_exp_f32_e32 v68, v65
	v_fma_f32 v65, v75, s33, -v232
	v_exp_f32_e32 v69, v65
	v_fma_f32 v65, v76, s33, -v232
	v_exp_f32_e32 v70, v65
	v_fma_f32 v65, v77, s33, -v232
	v_exp_f32_e32 v71, v65
	v_fma_f32 v65, v78, s33, -v232
	v_exp_f32_e32 v72, v65
	v_fma_f32 v65, v79, s33, -v232
	v_exp_f32_e32 v73, v65
	s_cbranch_vccz .LBB0_1037
	v_sub_f32_e32 v74, v234, v243
	v_exp_f32_e32 v74, v74
	s_nop 0
	v_pk_mul_f32 v[62:63], v[62:63], v[74:75] op_sel_hi:[1,0]
	v_pk_mul_f32 v[60:61], v[60:61], v[74:75] op_sel_hi:[1,0]
	v_pk_mul_f32 v[58:59], v[58:59], v[74:75] op_sel_hi:[1,0]
	v_pk_mul_f32 v[56:57], v[56:57], v[74:75] op_sel_hi:[1,0]
	v_pk_mul_f32 v[54:55], v[54:55], v[74:75] op_sel_hi:[1,0]
	v_pk_mul_f32 v[52:53], v[52:53], v[74:75] op_sel_hi:[1,0]
	v_pk_mul_f32 v[50:51], v[50:51], v[74:75] op_sel_hi:[1,0]
	v_pk_mul_f32 v[48:49], v[48:49], v[74:75] op_sel_hi:[1,0]
	v_pk_mul_f32 v[46:47], v[46:47], v[74:75] op_sel_hi:[1,0]
	v_pk_mul_f32 v[44:45], v[44:45], v[74:75] op_sel_hi:[1,0]
	v_pk_mul_f32 v[42:43], v[42:43], v[74:75] op_sel_hi:[1,0]
	v_pk_mul_f32 v[40:41], v[40:41], v[74:75] op_sel_hi:[1,0]
	v_pk_mul_f32 v[38:39], v[38:39], v[74:75] op_sel_hi:[1,0]
	v_pk_mul_f32 v[36:37], v[36:37], v[74:75] op_sel_hi:[1,0]
	v_pk_mul_f32 v[34:35], v[34:35], v[74:75] op_sel_hi:[1,0]
	v_pk_mul_f32 v[32:33], v[32:33], v[74:75] op_sel_hi:[1,0]
	v_pk_mul_f32 v[30:31], v[30:31], v[74:75] op_sel_hi:[1,0]
	v_pk_mul_f32 v[28:29], v[28:29], v[74:75] op_sel_hi:[1,0]
	v_pk_mul_f32 v[26:27], v[26:27], v[74:75] op_sel_hi:[1,0]
	v_pk_mul_f32 v[24:25], v[24:25], v[74:75] op_sel_hi:[1,0]
	v_pk_mul_f32 v[22:23], v[22:23], v[74:75] op_sel_hi:[1,0]
	v_pk_mul_f32 v[20:21], v[20:21], v[74:75] op_sel_hi:[1,0]
	v_pk_mul_f32 v[18:19], v[18:19], v[74:75] op_sel_hi:[1,0]
	v_pk_mul_f32 v[16:17], v[16:17], v[74:75] op_sel_hi:[1,0]
	v_pk_mul_f32 v[14:15], v[14:15], v[74:75] op_sel_hi:[1,0]
	v_pk_mul_f32 v[12:13], v[12:13], v[74:75] op_sel_hi:[1,0]
	v_pk_mul_f32 v[10:11], v[10:11], v[74:75] op_sel_hi:[1,0]
	v_pk_mul_f32 v[8:9], v[8:9], v[74:75] op_sel_hi:[1,0]
	v_pk_mul_f32 v[6:7], v[6:7], v[74:75] op_sel_hi:[1,0]
	v_pk_mul_f32 v[4:5], v[4:5], v[74:75] op_sel_hi:[1,0]
	v_pk_mul_f32 v[2:3], v[2:3], v[74:75] op_sel_hi:[1,0]
	v_pk_mul_f32 v[0:1], v[0:1], v[74:75] op_sel_hi:[1,0]
	v_mul_f32_e32 v183, v183, v74
; #define ATT_BAR() do { asm volatile("s_waitcnt lgkmcnt(0)" ::: "memory"); __builtin_amdgcn_s_barrier(); asm volatile("" ::: "memory"); } while (0)
; DI void attn_phase(const Params& p, const u16* proj, const char* prep, u16* obuf, char* smem) {
;     ...
;       if (grpB && kt + 1 < nt) { sstore((kt + 1) & 1); if (kt + 2 < nt) gload(kt + 2); }
;       ATT_BAR();
.LBB0_1037:
	s_add_i32 s12, s67, 1
	s_cmp_lt_i32 s12, s65
	s_cselect_b64 s[10:11], -1, 0
	s_and_b64 s[14:15], s[76:77], s[10:11]
	s_andn2_b64 vcc, exec, s[14:15]
	s_cbranch_vccnz .LBB0_1040
.LBB0_1040:
	s_waitcnt lgkmcnt(0)
	s_barrier
	s_andn2_b64 vcc, exec, s[76:77]
	s_cbranch_vccnz .Lskip_gl_b
	s_add_i32 s13, s67, 2
	s_cmp_ge_i32 s13, s65
	s_cbranch_scc1 .Lskip_gl_b
	v_add_u32_e32 v74, s78, v169
	v_mad_u64_u32 v[74:75], s[14:15], s86, v74, 0
	v_lshlrev_b64 v[74:75], 1, v[74:75]
	v_lshl_add_u64 v[76:77], v[192:193], 0, v[74:75]
	s_lshl_b64 s[14:15], s[78:79], 1
	v_lshl_add_u64 v[74:75], v[196:197], 0, v[74:75]
	global_load_dwordx4 v[128:131], v[76:77], off
	global_load_dwordx4 v[144:147], v[74:75], off
	v_lshl_add_u64 v[76:77], v[184:185], 0, s[14:15]
	v_lshl_add_u64 v[74:75], v[188:189], 0, s[14:15]
	global_load_dwordx4 v[132:135], v[76:77], off
	global_load_dwordx4 v[148:151], v[74:75], off
	v_add_u32_e32 v76, s78, v173
	v_add_u32_e32 v74, s78, v200
	v_mad_u64_u32 v[76:77], s[16:17], s86, v76, 0
	v_mad_u64_u32 v[74:75], s[16:17], s86, v74, 0
	v_lshl_add_u64 v[76:77], v[76:77], 1, v[194:195]
	v_lshl_add_u64 v[74:75], v[74:75], 1, v[198:199]
	global_load_dwordx4 v[136:139], v[76:77], off
	global_load_dwordx4 v[152:155], v[74:75], off
	v_lshl_add_u64 v[76:77], v[186:187], 0, s[14:15]
	v_lshl_add_u64 v[74:75], v[190:191], 0, s[14:15]
	global_load_dwordx4 v[140:143], v[76:77], off
	global_load_dwordx4 v[156:159], v[74:75], off
; #define MFMA(a, b, c) __builtin_amdgcn_mfma_f32_32x32x16_bf16((a), (b), (c), 0, 0, 0)
; DI void attn_phase(const Params& p, const u16* proj, const char* prep, u16* obuf, char* smem) {
;     ...
;       float rs = 0.f;
; #pragma unroll
;       for (int kti = 0; kti < 2; ++kti)
; #pragma unroll
;         for (int reg = 0; reg < 16; ++reg) {
;           const float pv = __builtin_amdgcn_exp2f(st[kti][reg] * SC - mn);
;           st[kti][reg] = pv; rs += pv;
;         }
;       rs += __shfl_xor(rs, 32);
;     ...
;       __builtin_amdgcn_s_setprio(1);
; #pragma unroll
;       for (int kti = 0; kti < 2; ++kti) {
;         {
;           const bf16x8 pf = packacc<0>(st[kti]);
; #pragma unroll
;           for (int vt = 0; vt < 4; ++vt) {
;             O[vt] = MFMA(ld16(Vt + ((vh * 4 + vt) * 32 + l31) * 72 + kti * 32 + 8 * hh), pf, O[vt]);
;           }
;         }
;         {
;           const bf16x8 pf = packacc<1>(st[kti]);
; #pragma unroll
;           for (int vt = 0; vt < 4; ++vt) {
;             O[vt] = MFMA(ld16(Vt + ((vh * 4 + vt) * 32 + l31) * 72 + kti * 32 + 16 + 8 * hh), pf, O[vt]);
;           }
;         }
;       }
;       __builtin_amdgcn_s_setprio(0);
;       if (!grpB && kt + 1 < nt) { sstore((kt + 1) & 1); if (kt + 2 < nt) gload(kt + 2); }
.Lskip_gl_b:
	s_setprio 1
	v_add_u32_e32 v233, v233, v226
	ds_read_b128 v[244:247], v233 offset:34816
	v_add_f32_e32 v64, v235, v236
	v_add_f32_e32 v78, v237, v238
	v_add_f32_e32 v79, v239, v240
	v_add_f32_e32 v234, v241, v242
	v_add_f32_e32 v64, v64, v80
	v_add_f32_e32 v78, v78, v81
	v_add_f32_e32 v79, v79, v82
	v_add_f32_e32 v234, v234, v83
	v_add_f32_e32 v64, v64, v84
	v_add_f32_e32 v78, v78, v85
	v_add_f32_e32 v79, v79, v87
	v_add_f32_e32 v234, v234, v89
	v_add_f32_e32 v64, v64, v86
	v_add_f32_e32 v78, v78, v88
	v_add_f32_e32 v79, v79, v90
	v_add_f32_e32 v234, v234, v91
	v_add_f32_e32 v64, v64, v92
	v_add_f32_e32 v78, v78, v93
	v_add_f32_e32 v79, v79, v94
	v_add_f32_e32 v234, v234, v95
	v_add_f32_e32 v64, v64, v66
	v_add_f32_e32 v78, v78, v67
	v_add_f32_e32 v79, v79, v68
	v_add_f32_e32 v234, v234, v69
	v_add_f32_e32 v64, v64, v70
	v_add_f32_e32 v78, v78, v71
	v_add_f32_e32 v79, v79, v72
	v_add_f32_e32 v234, v234, v73
	v_add_f32_e32 v64, v64, v78
	v_add_f32_e32 v79, v79, v234
	v_add_f32_e32 v64, v64, v79
	v_cvt_pk_bf16_f32 v74, v235, v236
	v_cvt_pk_bf16_f32 v75, v237, v238
	v_cvt_pk_bf16_f32 v76, v239, v240
	v_cvt_pk_bf16_f32 v77, v241, v242
	ds_read_b128 v[236:239], v233 offset:39424
	ds_read_b128 v[240:243], v233 offset:44032
	v_cvt_pk_bf16_f32 v80, v80, v81
	v_cvt_pk_bf16_f32 v81, v82, v83
	v_cvt_pk_bf16_f32 v82, v84, v85
	v_cvt_pk_bf16_f32 v83, v87, v89
	v_cvt_pk_bf16_f32 v84, v86, v88
	v_cvt_pk_bf16_f32 v85, v90, v91
	v_cvt_pk_bf16_f32 v86, v92, v93
	v_cvt_pk_bf16_f32 v87, v94, v95
	ds_read_b128 v[88:91], v233 offset:48640
	ds_read_b128 v[92:95], v233 offset:34848
	v_cvt_pk_bf16_f32 v66, v66, v67
	v_cvt_pk_bf16_f32 v67, v68, v69
	v_cvt_pk_bf16_f32 v68, v70, v71
	v_cvt_pk_bf16_f32 v69, v72, v73
	ds_read_b128 v[70:73], v233 offset:39456
	s_waitcnt lgkmcnt(5)
	v_mfma_f32_32x32x16_bf16 v[48:63], v[244:247], v[74:77], v[48:63]
	ds_read_b128 v[244:247], v233 offset:44064
	s_waitcnt lgkmcnt(5)
	v_mfma_f32_32x32x16_bf16 v[32:47], v[236:239], v[74:77], v[32:47]
	ds_read_b128 v[236:239], v233 offset:48672
	s_waitcnt lgkmcnt(5)
	v_mfma_f32_32x32x16_bf16 v[16:31], v[240:243], v[74:77], v[16:31]
	ds_read_b128 v[240:243], v233 offset:34880
	s_waitcnt lgkmcnt(5)
	v_mfma_f32_32x32x16_bf16 v[0:15], v[88:91], v[74:77], v[0:15]
	ds_read_b128 v[88:91], v233 offset:39488
	s_waitcnt lgkmcnt(5)
	v_mfma_f32_32x32x16_bf16 v[48:63], v[92:95], v[80:83], v[48:63]
	ds_read_b128 v[92:95], v233 offset:44096
	s_waitcnt lgkmcnt(5)
	v_mfma_f32_32x32x16_bf16 v[32:47], v[70:73], v[80:83], v[32:47]
	ds_read_b128 v[70:73], v233 offset:48704
	s_waitcnt lgkmcnt(5)
	v_mfma_f32_32x32x16_bf16 v[16:31], v[244:247], v[80:83], v[16:31]
	ds_read_b128 v[244:247], v233 offset:34912
	s_waitcnt lgkmcnt(5)
	v_mfma_f32_32x32x16_bf16 v[0:15], v[236:239], v[80:83], v[0:15]
	ds_read_b128 v[236:239], v233 offset:39520
	s_waitcnt lgkmcnt(5)
	v_mfma_f32_32x32x16_bf16 v[48:63], v[240:243], v[84:87], v[48:63]
	ds_read_b128 v[240:243], v233 offset:44128
	s_waitcnt lgkmcnt(5)
	v_mfma_f32_32x32x16_bf16 v[32:47], v[88:91], v[84:87], v[32:47]
	ds_read_b128 v[88:91], v233 offset:48736
	s_waitcnt lgkmcnt(5)
	v_mfma_f32_32x32x16_bf16 v[16:31], v[92:95], v[84:87], v[16:31]
	s_waitcnt lgkmcnt(4)
	v_mfma_f32_32x32x16_bf16 v[0:15], v[70:73], v[84:87], v[0:15]
	s_waitcnt lgkmcnt(3)
	v_mfma_f32_32x32x16_bf16 v[48:63], v[244:247], v[66:69], v[48:63]
	s_waitcnt lgkmcnt(2)
	v_mfma_f32_32x32x16_bf16 v[32:47], v[236:239], v[66:69], v[32:47]
	s_waitcnt lgkmcnt(1)
	v_mfma_f32_32x32x16_bf16 v[16:31], v[240:243], v[66:69], v[16:31]
	s_waitcnt lgkmcnt(0)
	v_mfma_f32_32x32x16_bf16 v[0:15], v[88:91], v[66:69], v[0:15]
	ds_bpermute_b32 v65, v181, v64
	s_setprio 0
	s_and_b64 s[10:11], s[72:73], s[10:11]
	s_andn2_b64 vcc, exec, s[10:11]
	s_cbranch_vccnz .LBB0_1043
	s_bitcmp1_b32 s12, 0
	s_cselect_b32 s10, 0x11800, 0
	s_add_i32 s10, s10, 0
	v_add3_u32 v66, s10, v201, v162
	s_waitcnt vmcnt(7)
	ds_write_b128 v66, v[128:131]
	v_add3_u32 v66, s10, v203, v182
	s_waitcnt vmcnt(5)
	ds_write_b128 v66, v[132:135] offset:34816
	v_add3_u32 v66, s10, v205, v162
	s_waitcnt vmcnt(3)
	ds_write_b128 v66, v[136:139]
	v_add3_u32 v66, s10, v207, v182
	s_waitcnt vmcnt(1)
	ds_write_b128 v66, v[140:143] offset:34816
	v_add3_u32 v66, s10, v211, v162
	ds_write_b128 v66, v[144:147]
	v_add3_u32 v66, s10, v213, v182
	ds_write_b128 v66, v[148:151] offset:34816
	v_add3_u32 v66, s10, v215, v162
	ds_write_b128 v66, v[152:155]
	v_add3_u32 v66, s10, v217, v182
	s_add_i32 s10, s67, 2
	s_cmp_ge_i32 s10, s65
	s_waitcnt vmcnt(0)
	ds_write_b128 v66, v[156:159] offset:34816
	s_cbranch_scc1 .LBB0_1043
	v_add_u32_e32 v66, s78, v169
	v_mad_u64_u32 v[66:67], s[10:11], s86, v66, 0
	v_lshlrev_b64 v[66:67], 1, v[66:67]
	v_lshl_add_u64 v[68:69], v[192:193], 0, v[66:67]
	s_lshl_b64 s[10:11], s[78:79], 1
	v_lshl_add_u64 v[66:67], v[196:197], 0, v[66:67]
	global_load_dwordx4 v[128:131], v[68:69], off
	global_load_dwordx4 v[144:147], v[66:67], off
	v_lshl_add_u64 v[68:69], v[184:185], 0, s[10:11]
	v_lshl_add_u64 v[66:67], v[188:189], 0, s[10:11]
	global_load_dwordx4 v[132:135], v[68:69], off
	global_load_dwordx4 v[148:151], v[66:67], off
	v_add_u32_e32 v68, s78, v173
	v_add_u32_e32 v66, s78, v200
	v_mad_u64_u32 v[68:69], s[14:15], s86, v68, 0
	v_mad_u64_u32 v[66:67], s[14:15], s86, v66, 0
	v_lshl_add_u64 v[68:69], v[68:69], 1, v[194:195]
	v_lshl_add_u64 v[66:67], v[66:67], 1, v[198:199]
	global_load_dwordx4 v[136:139], v[68:69], off
	global_load_dwordx4 v[152:155], v[66:67], off
	v_lshl_add_u64 v[68:69], v[186:187], 0, s[10:11]
	v_lshl_add_u64 v[66:67], v[190:191], 0, s[10:11]
	global_load_dwordx4 v[140:143], v[68:69], off
	global_load_dwordx4 v[156:159], v[66:67], off
